# grid barrier: every workgroup polls the cross-XCC counter (no returning atomic on it, no per-XCC generation hop)
# baseline (speedup 1.0000x reference)
.LBB0_649:
	v_readlane_b32 s6, v253, 50
	s_add_u32 s57, s4, s6
	s_addc_u32 s56, s5, 0
	v_mov_b32_e32 v1, s57
	v_add_co_u32_e32 v4, vcc, 0x1000, v1
	v_mov_b32_e32 v1, s56
	s_nop 0
	v_addc_co_u32_e32 v5, vcc, 0, v1, vcc
	flat_atomic_add v3, v[4:5], v202 offset:1024 sc0
	v_cvt_f32_u32_e32 v1, v2
	v_sub_u32_e32 v4, 0, v2
	v_rcp_iflag_f32_e32 v1, v1
	s_nop 0
	v_mul_f32_e32 v1, 0x4f7ffffe, v1
	v_cvt_u32_f32_e32 v1, v1
	v_mul_lo_u32 v4, v4, v1
	v_mul_hi_u32 v4, v1, v4
	v_add_u32_e32 v1, v1, v4
	s_waitcnt vmcnt(0) lgkmcnt(0)
	v_mul_hi_u32 v1, v3, v1
	v_mul_lo_u32 v4, v1, v2
	v_sub_u32_e32 v4, v3, v4
	v_cmp_ge_u32_e32 vcc, v4, v2
	v_add_u32_e32 v5, 1, v1
	s_nop 0
	v_cndmask_b32_e32 v1, v1, v5, vcc
	v_sub_u32_e32 v5, v4, v2
	v_cndmask_b32_e32 v4, v4, v5, vcc
	v_cmp_ge_u32_e32 vcc, v4, v2
	v_add_u32_e32 v4, 1, v1
	s_nop 0
	v_cndmask_b32_e32 v1, v1, v4, vcc
	v_add_u32_e32 v4, 1, v3
	v_mad_u64_u32 v[2:3], s[6:7], v2, v1, v[2:3]
	v_cmp_ne_u32_e32 vcc, v4, v2
	v_mad_u64_u32 v[26:27], s[6:7], v0, v1, v[0:1]
	s_add_u32 s6, s4, 0x3000
	s_addc_u32 s7, s5, 0
	v_mov_b64_e32 v[20:21], s[6:7]
	s_cbranch_vccnz .Lgb_spin
	s_lshr_b32 s98, 0x160580, s14
	s_and_b32 s98, s98, 1
	v_readlane_b32 s99, v255, 59
	s_and_b32 s98, s98, s99
	s_cmp_eq_u32 s98, 1
	s_cbranch_scc1 .Lwb_skip
	buffer_wbl2 sc1
.Lwb_skip:
	s_waitcnt vmcnt(0)
	flat_atomic_add v[20:21], v202 offset:1024
	s_branch .Lgb_spin

.Lgb_spin:
	s_mov_b32 s58, 0
.Lgb_spin_loop:
	flat_load_dword v22, v[20:21] offset:1024 sc1
	s_waitcnt vmcnt(0) lgkmcnt(0)
	v_sub_u32_e32 v22, v22, v26
	v_cmp_gt_i32_e32 vcc, 0, v22
	s_cbranch_vccz .Lgb_acq
	s_sleep 1
	s_add_i32 s58, s58, 1
	s_cmp_lt_u32 s58, 0x40001
	s_cbranch_scc1 .Lgb_spin_loop
